# sync points 64/88
# baseline (speedup 1.0000x reference)
; template <bool INSYNC> DI void mlstm_phase(const Ctx& C, const bf16* PROJ, const f32x4* TAB, const bf16* PP, bf16* HF, bf16* HB, const XcdBarrier& xbar) {
;     ...
;         for (int c = 0; c < SEQ / 64; ++c) {
;             if (INSYNC && (c == 43 || c == 86)) xcd_barrier(xbar);
.LBB0_1403:
	s_mov_b32 s35, s22
	s_cmpk_lt_i32 s22, 0x58
	s_cbranch_scc1 .LBB0_1405
	s_cmpk_eq_i32 s35, 0x58
	s_cselect_b64 s[20:21], -1, 0
	s_cbranch_execz .LBB0_1406
	s_branch .LBB0_1407

; template <bool INSYNC> DI void mlstm_phase(const Ctx& C, const bf16* PROJ, const f32x4* TAB, const bf16* PP, bf16* HF, bf16* HB, const XcdBarrier& xbar) {
;     ...
;         for (int c = 0; c < SEQ / 64; ++c) {
;             if (INSYNC && (c == 43 || c == 86)) xcd_barrier(xbar);
.LBB0_1406:
	s_cmp_eq_u32 s35, 64
	s_cselect_b64 s[20:21], -1, 0
